# S14 plus attention unit prologue: the 12 Q-fragment vmcnt waits moved from one block after the barrier to the first MFMA that consumes each fragment (waits to first consumer)
# speedup vs baseline: 1.0031x; 1.0031x over previous
; #define ATT_LOADK(t) do { rk0 = *(const u32x4*)(gk + (size_t)(64 * (t)) * NKN); rk1 = *(const u32x4*)(gk + (size_t)(64 * (t) + 32) * NKN); rr = *(const u32x4*)(gr + (size_t)(64 * (t)) * 64); } while (0)
; #define ATT_LOADV(t) do { rv0 = *(const u32x4*)(gv + 64 * (t)); rv1 = *(const u32x4*)(gv + (size_t)64 * M + 64 * (t)); } while (0)
; #define ATT_STOREK(ko) do { *(LAS u32x4*)(lds + (ko) + lk) = rk0; *(LAS u32x4*)(lds + (ko) + lk + 32 * KROW) = rk1; *(LAS u32x4*)(lds + (ko) + lr) = rr; } while (0)
; #define ATT_STOREV(vo) do { *(LAS u32x2*)(lds + (vo) + lv) = (u32x2){rv0.x, rv0.y}; *(LAS u32x2*)(lds + (vo) + lv + 8) = (u32x2){rv0.z, rv0.w}; \
;         *(LAS u32x2*)(lds + (vo) + lv + 64 * VROW) = (u32x2){rv1.x, rv1.y}; *(LAS u32x2*)(lds + (vo) + lv + 64 * VROW + 8) = (u32x2){rv1.z, rv1.w}; } while (0)
; __device__ __forceinline__ void unit(LAS unsigned char* lds, int b, int h, int qb, const bf16_t* Q, const bf16_t* Kn, const bf16_t* Kr, const bf16_t* VT, const bf16_t* proj, bf16_t* ymix, int wv) {
;     ...
;     const int tok0 = b * SEQ, q0 = qb * 256, NT = 4 * (qb + 1);
;     bf16x8 qf[12];
;     { const bf16_t* qp = Q + (size_t)(tok0 + q0 + 32 * wave + l32) * NQ + h * 192 + 8 * hi;
; #pragma unroll
;       for (int ks = 0; ks < 12; ++ks) qf[ks] = *(const bf16x8*)(qp + 16 * ks); }
;     const bf16_t* gk = Kn + (size_t)(tok0 + (tid >> 4)) * NKN + h * 128 + (tid & 15) * 8;
;     const bf16_t* gr = Kr + (size_t)(tok0 + (tid >> 3)) * 64 + (tid & 7) * 8;
;     const bf16_t* gv = VT + (size_t)(h * 128 + (tid >> 3)) * M + tok0 + (tid & 7) * 8;
;     const int lk = LDS_K + (tid >> 4) * KROW + (tid & 15) * 16, lr = LDS_K + (tid >> 3) * KROW + 256 + (tid & 7) * 16, lv = LDS_V + (tid >> 3) * VROW + (tid & 7) * 16;
;     u32x4 rk0, rk1, rr, rv0, rv1;
;     ...
;     f32x16 o[4];
; #pragma unroll
;     for (int i = 0; i < 4; ++i) o[i] = (f32x16){0, 0, 0, 0, 0, 0, 0, 0, 0, 0, 0, 0, 0, 0, 0, 0};
;     float mrun = -INFINITY, lrun = 0.f;
;     const int qidx = q0 + 32 * wave + l32;
;     f32x16 p0, p1; bf16x8 pf[2][2];
;     ...
;     ATT_LOADK(0); ATT_LOADV(0); ATT_STOREK(0); ATT_STOREV(0);
;     ATT_LOADK(1); ATT_STOREK(KBUF);
;     __syncthreads();
; #pragma unroll
;     for (int ks = 0; ks < 12; ++ks) asm volatile("" : "+v"(qf[ks]));
.LBB0_606:
	s_ashr_i32 s55, s68, 8
	s_and_b32 s8, s68, 1
	s_cmp_lt_i32 s55, 2
	s_cselect_b32 s9, 7, 3
	s_cmp_eq_u32 s8, 0
	s_cselect_b32 s63, s9, 5
	s_sub_i32 s62, s63, s55
	s_lshl_b32 s8, s68, 7
	s_and_b32 s54, s8, 0x7800
	s_lshl_b32 s8, s62, 8
	v_readlane_b32 s10, v254, 20
	v_mov_b32_e32 v0, v223
	s_add_i32 s8, s8, s10
	s_bfe_u32 s9, s68, 0x30001
	s_add_i32 s12, s8, s54
	v_and_b32_e32 v50, 31, v0
	v_or_b32_e32 v2, s12, v50
	s_movk_i32 s12, 0xc00
	s_lshl_b32 s69, s9, 7
	v_ashrrev_i32_e32 v33, 3, v0
	v_mad_i64_i32 v[2:3], s[14:15], v2, s12, v[204:205]
	s_mul_i32 s12, s9, 0x180
	v_ashrrev_i32_e32 v32, 4, v0
	v_add_u32_e32 v6, s69, v33
	v_lshl_add_u64 v[22:23], v[2:3], 0, s[12:13]
	v_add_u32_e32 v2, s54, v32
	v_ashrrev_i32_e32 v7, 31, v6
	v_ashrrev_i32_e32 v3, 31, v2
	v_lshlrev_b64 v[6:7], 16, v[6:7]
	v_lshlrev_b64 v[2:3], 11, v[2:3]
	v_add_u32_e32 v4, s54, v33
	v_lshl_add_u64 v[6:7], s[56:57], 0, v[6:7]
	s_lshl_b32 s12, s54, 1
	v_ashrrev_i32_e32 v5, 31, v4
	v_lshl_add_u64 v[6:7], v[6:7], 0, s[12:13]
	v_lshlrev_b32_e32 v8, 4, v0
	v_lshl_add_u64 v[2:3], s[52:53], 0, v[2:3]
	s_lshl_b32 s12, s9, 8
	v_lshlrev_b64 v[4:5], 7, v[4:5]
	v_and_b32_e32 v26, 0xf0, v8
	v_lshl_add_u64 v[2:3], v[2:3], 0, s[12:13]
	v_mov_b32_e32 v27, v1
	v_and_b32_e32 v24, 0x70, v8
	v_mov_b32_e32 v25, v1
	v_lshl_add_u64 v[208:209], v[2:3], 0, v[26:27]
	v_lshl_add_u64 v[2:3], s[48:49], 0, v[4:5]
	s_mov_b32 s9, 0x10000
	v_lshl_add_u64 v[210:211], v[2:3], 0, v[24:25]
	v_add_co_u32_e32 v2, vcc, s9, v208
	v_lshl_add_u64 v[206:207], v[6:7], 0, v[24:25]
	s_nop 0
	v_addc_co_u32_e32 v3, vcc, 0, v209, vcc
	v_add_co_u32_e32 v18, vcc, s37, v206
	global_load_dwordx4 v[2:5], v[2:3], off
	s_nop 0
	global_load_dwordx4 v[6:9], v[210:211], off
	global_load_dwordx4 v[10:13], v[208:209], off
	global_load_dwordx4 v[14:17], v[206:207], off
	v_addc_co_u32_e32 v19, vcc, 0, v207, vcc
	v_add_co_u32_e32 v28, vcc, s43, v208
	v_bfe_u32 v51, v0, 5, 1
	s_nop 0
	v_addc_co_u32_e32 v29, vcc, 0, v209, vcc
	global_load_dwordx4 v[18:21], v[18:19], off
	s_nop 0
	global_load_dwordx4 v[176:179], v[28:29], off
	v_add_co_u32_e32 v28, vcc, s44, v208
	v_lshlrev_b32_e32 v0, 4, v51
	s_nop 0
	v_addc_co_u32_e32 v29, vcc, 0, v209, vcc
	v_add_co_u32_e32 v30, vcc, s45, v210
	v_lshl_add_u64 v[22:23], v[22:23], 0, v[0:1]
	s_nop 0
	v_addc_co_u32_e32 v31, vcc, 0, v211, vcc
	global_load_dwordx4 v[184:187], v[28:29], off
	global_load_dwordx4 v[188:191], v[30:31], off
	global_load_dwordx4 v[128:131], v[22:23], off
	global_load_dwordx4 v[132:135], v[22:23], off offset:32
	global_load_dwordx4 v[136:139], v[22:23], off offset:64
	global_load_dwordx4 v[140:143], v[22:23], off offset:96
	global_load_dwordx4 v[144:147], v[22:23], off offset:128
	global_load_dwordx4 v[148:151], v[22:23], off offset:160
	global_load_dwordx4 v[152:155], v[22:23], off offset:192
	global_load_dwordx4 v[156:159], v[22:23], off offset:224
	global_load_dwordx4 v[160:163], v[22:23], off offset:256
	global_load_dwordx4 v[164:167], v[22:23], off offset:288
	global_load_dwordx4 v[168:171], v[22:23], off offset:320
	global_load_dwordx4 v[172:175], v[22:23], off offset:352
	s_movk_i32 s9, 0x88
	v_mad_u64_u32 v[212:213], s[14:15], v32, s27, v[26:27]
	v_mul_lo_u32 v22, v33, s9
	v_add_u32_e32 v23, 0, v212
	v_mad_u64_u32 v[214:215], s[14:15], v33, s27, v[24:25]
	s_cmp_lg_u32 s63, s55
	s_cselect_b64 s[58:59], -1, 0
	s_mov_b64 s[60:61], -1
	s_and_b64 vcc, exec, s[58:59]
	s_waitcnt vmcnt(17)
	ds_write_b128 v23, v[10:13]
	ds_write_b128 v23, v[2:5] offset:12800
	v_add_u32_e32 v3, 0, v22
	v_add3_u32 v213, v3, v24, s42
	v_add_u32_e32 v2, 0, v214
	v_add_u32_e32 v3, 0x2200, v213
	ds_write_b128 v2, v[6:9] offset:256
	s_waitcnt vmcnt(16)
	ds_write2_b64 v213, v[14:15], v[16:17] offset1:1
	s_waitcnt vmcnt(15)
	ds_write2_b64 v3, v[18:19], v[20:21] offset1:1
	s_waitcnt vmcnt(14)
	ds_write_b128 v23, v[176:179] offset:25600
	s_waitcnt vmcnt(13)
	ds_write_b128 v23, v[184:187] offset:38400
	s_waitcnt vmcnt(12)
	ds_write_b128 v2, v[188:191] offset:25856
	v_mul_u32_u24_e32 v2, 0x190, v50
	v_add3_u32 v215, 0, v2, v0
	s_waitcnt lgkmcnt(0)
	s_barrier
	ds_read_b128 v[2:5], v215
	ds_read_b128 v[34:37], v215 offset:32
	s_waitcnt lgkmcnt(1)
	s_waitcnt vmcnt(11)
	v_mfma_f32_32x32x16_bf16 v[2:17], v[2:5], v[128:131], 0
	ds_read_b128 v[18:21], v215 offset:12800
	ds_read_b128 v[38:41], v215 offset:12832
	s_waitcnt lgkmcnt(1)
	v_mfma_f32_32x32x16_bf16 v[18:33], v[18:21], v[128:131], 0
	s_waitcnt vmcnt(10)
	v_mfma_f32_32x32x16_bf16 v[2:17], v[34:37], v[132:135], v[2:17]
	s_waitcnt lgkmcnt(0)
	v_mfma_f32_32x32x16_bf16 v[18:33], v[38:41], v[132:135], v[18:33]
	ds_read_b128 v[34:37], v215 offset:64
	ds_read_b128 v[38:41], v215 offset:96
	s_waitcnt lgkmcnt(1)
	s_waitcnt vmcnt(9)
	v_mfma_f32_32x32x16_bf16 v[2:17], v[34:37], v[136:139], v[2:17]
	ds_read_b128 v[34:37], v215 offset:12864
	ds_read_b128 v[42:45], v215 offset:12896
	s_waitcnt lgkmcnt(1)
	v_mfma_f32_32x32x16_bf16 v[18:33], v[34:37], v[136:139], v[18:33]
	s_waitcnt vmcnt(8)
	v_mfma_f32_32x32x16_bf16 v[2:17], v[38:41], v[140:143], v[2:17]
	ds_read_b128 v[34:37], v215 offset:128
	ds_read_b128 v[38:41], v215 offset:160
	s_waitcnt lgkmcnt(2)
	v_mfma_f32_32x32x16_bf16 v[18:33], v[42:45], v[140:143], v[18:33]
	s_waitcnt lgkmcnt(1)
	s_waitcnt vmcnt(7)
	v_mfma_f32_32x32x16_bf16 v[2:17], v[34:37], v[144:147], v[2:17]
	ds_read_b128 v[34:37], v215 offset:12928
	ds_read_b128 v[42:45], v215 offset:12960
	s_waitcnt lgkmcnt(1)
	v_mfma_f32_32x32x16_bf16 v[18:33], v[34:37], v[144:147], v[18:33]
	s_waitcnt vmcnt(6)
	v_mfma_f32_32x32x16_bf16 v[2:17], v[38:41], v[148:151], v[2:17]
	ds_read_b128 v[34:37], v215 offset:192
	ds_read_b128 v[38:41], v215 offset:224
	s_waitcnt lgkmcnt(2)
; __device__ __forceinline__ void unit(LAS unsigned char* lds, int b, int h, int qb, const bf16_t* Q, const bf16_t* Kn, const bf16_t* Kr, const bf16_t* VT, const bf16_t* proj, bf16_t* ymix, int wv) {
;     ...
;     ATT_QK(0);
;     if (NT <= 4) ATT_SMA(0, true); else ATT_SMA(0, false);
;     pf[0][0] = pf2[0][0]; pf[0][1] = pf2[0][1]; pf[1][0] = pf2[1][0]; pf[1][1] = pf2[1][1];
	v_mfma_f32_32x32x16_bf16 v[18:33], v[42:45], v[148:151], v[18:33]
	s_waitcnt lgkmcnt(1)
	s_waitcnt vmcnt(5)
	v_mfma_f32_32x32x16_bf16 v[2:17], v[34:37], v[152:155], v[2:17]
	ds_read_b128 v[34:37], v215 offset:12992
	ds_read_b128 v[42:45], v215 offset:13024
	s_waitcnt lgkmcnt(1)
	v_mfma_f32_32x32x16_bf16 v[18:33], v[34:37], v[152:155], v[18:33]
	s_waitcnt vmcnt(4)
	v_mfma_f32_32x32x16_bf16 v[2:17], v[38:41], v[156:159], v[2:17]
	ds_read_b128 v[34:37], v215 offset:256
	ds_read_b128 v[38:41], v215 offset:288
	s_waitcnt lgkmcnt(2)
	v_mfma_f32_32x32x16_bf16 v[18:33], v[42:45], v[156:159], v[18:33]
	s_waitcnt lgkmcnt(1)
	s_waitcnt vmcnt(3)
	v_mfma_f32_32x32x16_bf16 v[2:17], v[34:37], v[160:163], v[2:17]
	ds_read_b128 v[34:37], v215 offset:13056
	ds_read_b128 v[42:45], v215 offset:13088
	s_waitcnt lgkmcnt(1)
	v_mfma_f32_32x32x16_bf16 v[18:33], v[34:37], v[160:163], v[18:33]
	s_waitcnt vmcnt(2)
	v_mfma_f32_32x32x16_bf16 v[2:17], v[38:41], v[164:167], v[2:17]
	ds_read_b128 v[34:37], v215 offset:320
	ds_read_b128 v[38:41], v215 offset:352
	s_waitcnt lgkmcnt(2)
	v_mfma_f32_32x32x16_bf16 v[18:33], v[42:45], v[164:167], v[18:33]
	s_waitcnt lgkmcnt(1)
	s_waitcnt vmcnt(1)
	v_mfma_f32_32x32x16_bf16 v[2:17], v[34:37], v[168:171], v[2:17]
	ds_read_b128 v[34:37], v215 offset:13120
	ds_read_b128 v[42:45], v215 offset:13152
	s_waitcnt lgkmcnt(1)
	v_mfma_f32_32x32x16_bf16 v[18:33], v[34:37], v[168:171], v[18:33]
	s_waitcnt vmcnt(0)
	v_mfma_f32_32x32x16_bf16 v[2:17], v[38:41], v[172:175], v[2:17]
	s_waitcnt lgkmcnt(0)
	v_mfma_f32_32x32x16_bf16 v[18:33], v[42:45], v[172:175], v[18:33]
	s_cbranch_vccz .LBB0_608
	s_nop 10
	v_max_f32_e32 v0, v19, v19
	v_max_f32_e32 v34, v3, v3
	v_max_f32_e32 v0, v34, v0
	v_max_f32_e32 v34, v20, v20
	v_max_f32_e32 v35, v4, v4
	v_max_f32_e32 v34, v35, v34
	v_max_f32_e32 v35, v21, v21
	v_max_f32_e32 v36, v5, v5
	v_max3_f32 v0, v2, v18, v0
	v_max_f32_e32 v35, v36, v35
	v_max3_f32 v0, v0, v34, v35
	v_max_f32_e32 v34, v22, v22
	v_max_f32_e32 v35, v6, v6
	v_max_f32_e32 v34, v35, v34
	v_max_f32_e32 v35, v23, v23
	v_max_f32_e32 v36, v7, v7
	v_max_f32_e32 v35, v36, v35
	v_max3_f32 v0, v0, v34, v35
	v_max_f32_e32 v34, v24, v24
	v_max_f32_e32 v35, v8, v8
	v_max_f32_e32 v34, v35, v34
	v_max_f32_e32 v35, v25, v25
	v_max_f32_e32 v36, v9, v9
	v_max_f32_e32 v35, v36, v35
	v_max3_f32 v0, v0, v34, v35
	v_max_f32_e32 v34, v26, v26
	v_max_f32_e32 v35, v10, v10
	v_max_f32_e32 v34, v35, v34
	v_max_f32_e32 v35, v27, v27
	v_max_f32_e32 v36, v11, v11
	v_max_f32_e32 v35, v36, v35
	v_max3_f32 v0, v0, v34, v35
	v_max_f32_e32 v34, v28, v28
	v_max_f32_e32 v35, v12, v12
	v_max_f32_e32 v34, v35, v34
	v_max_f32_e32 v35, v29, v29
	v_max_f32_e32 v36, v13, v13
	v_max_f32_e32 v35, v36, v35
	v_max3_f32 v0, v0, v34, v35
	v_max_f32_e32 v34, v30, v30
	v_max_f32_e32 v35, v14, v14
	v_max_f32_e32 v34, v35, v34
	v_max_f32_e32 v35, v31, v31
	v_max_f32_e32 v36, v15, v15
	v_max_f32_e32 v35, v36, v35
	v_max3_f32 v0, v0, v34, v35
	v_max_f32_e32 v34, v32, v32
	v_max_f32_e32 v35, v16, v16
	v_max_f32_e32 v34, v35, v34
	v_max_f32_e32 v35, v33, v33
	v_max_f32_e32 v36, v17, v17
	v_max_f32_e32 v35, v36, v35
	v_max3_f32 v0, v0, v34, v35
	v_mov_b32_e32 v34, v222
	s_mov_b64 s[60:61], 0
	v_lshlrev_b32_e32 v34, 2, v34
	v_xor_b32_e32 v34, 0x80, v34
	ds_bpermute_b32 v34, v34, v0
	s_waitcnt lgkmcnt(0)
	v_max3_f32 v217, v0, v34, s64
	v_sub_f32_e32 v34, v2, v217
	v_sub_f32_e32 v42, v10, v217
	v_exp_f32_e32 v52, v34
	v_sub_f32_e32 v34, v18, v217
	v_exp_f32_e32 v68, v42
	v_sub_f32_e32 v42, v26, v217
	v_exp_f32_e32 v54, v34
	v_sub_f32_e32 v34, v3, v217
	v_exp_f32_e32 v70, v42
	v_sub_f32_e32 v42, v11, v217
	v_exp_f32_e32 v53, v34
	v_sub_f32_e32 v34, v19, v217
	v_exp_f32_e32 v69, v42
	v_sub_f32_e32 v42, v27, v217
	v_exp_f32_e32 v55, v34
	v_sub_f32_e32 v34, v4, v217
	v_exp_f32_e32 v71, v42
	v_sub_f32_e32 v42, v12, v217
	v_exp_f32_e32 v56, v34
	v_sub_f32_e32 v34, v20, v217
	v_exp_f32_e32 v72, v42
	v_sub_f32_e32 v42, v28, v217
	v_exp_f32_e32 v58, v34
	v_sub_f32_e32 v34, v5, v217
	v_exp_f32_e32 v74, v42
	v_sub_f32_e32 v42, v13, v217
	v_exp_f32_e32 v57, v34
	v_sub_f32_e32 v34, v21, v217
	v_exp_f32_e32 v73, v42
	v_sub_f32_e32 v42, v29, v217
	v_exp_f32_e32 v59, v34
	v_sub_f32_e32 v34, v6, v217
	v_exp_f32_e32 v75, v42
	v_sub_f32_e32 v42, v14, v217
	v_exp_f32_e32 v60, v34
	v_sub_f32_e32 v34, v22, v217
	v_exp_f32_e32 v76, v42
	v_sub_f32_e32 v42, v30, v217
	v_exp_f32_e32 v62, v34
	v_sub_f32_e32 v34, v7, v217
	v_exp_f32_e32 v78, v42
	v_sub_f32_e32 v42, v15, v217
	v_exp_f32_e32 v61, v34
	v_sub_f32_e32 v34, v23, v217
	v_exp_f32_e32 v77, v42
	v_sub_f32_e32 v42, v31, v217
	v_exp_f32_e32 v63, v34
	v_sub_f32_e32 v34, v8, v217
	v_exp_f32_e32 v79, v42
	v_sub_f32_e32 v42, v16, v217
	v_exp_f32_e32 v64, v34
	v_sub_f32_e32 v34, v24, v217
	v_exp_f32_e32 v80, v42
	v_sub_f32_e32 v42, v32, v217
	v_exp_f32_e32 v66, v34
	v_sub_f32_e32 v34, v9, v217
	v_exp_f32_e32 v82, v42
	v_sub_f32_e32 v42, v17, v217
	v_exp_f32_e32 v65, v34
	v_sub_f32_e32 v34, v25, v217
	v_exp_f32_e32 v81, v42
	v_sub_f32_e32 v42, v33, v217
	v_exp_f32_e32 v67, v34
	v_exp_f32_e32 v83, v42
	v_sub_f32_e32 v0, 0xff800000, v217
	v_pk_add_f32 v[38:39], v[54:55], v[52:53]
	v_pk_add_f32 v[36:37], v[58:59], v[56:57]
	v_pk_add_f32 v[34:35], v[62:63], v[60:61]
	v_pk_add_f32 v[40:41], v[66:67], v[64:65]
	v_pk_add_f32 v[46:47], v[70:71], v[68:69]
	v_pk_add_f32 v[44:45], v[74:75], v[72:73]
	v_pk_add_f32 v[42:43], v[78:79], v[76:77]
	v_pk_add_f32 v[48:49], v[82:83], v[80:81]
	v_exp_f32_e32 v0, v0
	v_cvt_pk_bf16_f32 v200, v52, v53
	v_cvt_pk_bf16_f32 v201, v56, v57
	v_cvt_pk_bf16_f32 v202, v60, v61
	v_cvt_pk_bf16_f32 v203, v64, v65
	v_cvt_pk_bf16_f32 v192, v54, v55
	v_cvt_pk_bf16_f32 v193, v58, v59
	v_cvt_pk_bf16_f32 v194, v62, v63
	v_cvt_pk_bf16_f32 v195, v66, v67
	v_cvt_pk_bf16_f32 v196, v68, v69
	v_cvt_pk_bf16_f32 v197, v72, v73
	v_cvt_pk_bf16_f32 v198, v76, v77
	v_cvt_pk_bf16_f32 v199, v80, v81
	v_cvt_pk_bf16_f32 v180, v70, v71
	v_cvt_pk_bf16_f32 v181, v74, v75
	v_cvt_pk_bf16_f32 v182, v78, v79
	v_cvt_pk_bf16_f32 v183, v82, v83

; #define ATT_LOADK(t) do { rk0 = *(const u32x4*)(gk + (size_t)(64 * (t)) * NKN); rk1 = *(const u32x4*)(gk + (size_t)(64 * (t) + 32) * NKN); rr = *(const u32x4*)(gr + (size_t)(64 * (t)) * 64); } while (0)
; #define ATT_LOADV(t) do { rv0 = *(const u32x4*)(gv + 64 * (t)); rv1 = *(const u32x4*)(gv + (size_t)64 * M + 64 * (t)); } while (0)
; #define ATT_STOREK(ko) do { *(LAS u32x4*)(lds + (ko) + lk) = rk0; *(LAS u32x4*)(lds + (ko) + lk + 32 * KROW) = rk1; *(LAS u32x4*)(lds + (ko) + lr) = rr; } while (0)
; #define ATT_STOREV(vo) do { *(LAS u32x2*)(lds + (vo) + lv) = (u32x2){rv0.x, rv0.y}; *(LAS u32x2*)(lds + (vo) + lv + 8) = (u32x2){rv0.z, rv0.w}; \
;         *(LAS u32x2*)(lds + (vo) + lv + 64 * VROW) = (u32x2){rv1.x, rv1.y}; *(LAS u32x2*)(lds + (vo) + lv + 64 * VROW + 8) = (u32x2){rv1.z, rv1.w}; } while (0)
; __device__ __forceinline__ void unit(LAS unsigned char* lds, int b, int h, int qb, const bf16_t* Q, const bf16_t* Kn, const bf16_t* Kr, const bf16_t* VT, const bf16_t* proj, bf16_t* ymix, int wv) {
;     ...
;     const int tok0 = b * SEQ, q0 = qb * 256, NT = 4 * (qb + 1);
;     bf16x8 qf[12];
;     { const bf16_t* qp = Q + (size_t)(tok0 + q0 + 32 * wave + l32) * NQ + h * 192 + 8 * hi;
; #pragma unroll
;       for (int ks = 0; ks < 12; ++ks) qf[ks] = *(const bf16x8*)(qp + 16 * ks); }
;     const bf16_t* gk = Kn + (size_t)(tok0 + (tid >> 4)) * NKN + h * 128 + (tid & 15) * 8;
;     const bf16_t* gr = Kr + (size_t)(tok0 + (tid >> 3)) * 64 + (tid & 7) * 8;
;     const bf16_t* gv = VT + (size_t)(h * 128 + (tid >> 3)) * M + tok0 + (tid & 7) * 8;
;     const int lk = LDS_K + (tid >> 4) * KROW + (tid & 15) * 16, lr = LDS_K + (tid >> 3) * KROW + 256 + (tid & 7) * 16, lv = LDS_V + (tid >> 3) * VROW + (tid & 7) * 16;
;     u32x4 rk0, rk1, rr, rv0, rv1;
;     ...
;     f32x16 o[4];
; #pragma unroll
;     for (int i = 0; i < 4; ++i) o[i] = (f32x16){0, 0, 0, 0, 0, 0, 0, 0, 0, 0, 0, 0, 0, 0, 0, 0};
;     float mrun = -INFINITY, lrun = 0.f;
;     const int qidx = q0 + 32 * wave + l32;
;     f32x16 p0, p1; bf16x8 pf[2][2];
;     ...
;     ATT_LOADK(0); ATT_LOADV(0); ATT_STOREK(0); ATT_STOREV(0);
;     ATT_LOADK(1); ATT_STOREK(KBUF);
;     __syncthreads();
; #pragma unroll
;     for (int ks = 0; ks < 12; ++ks) asm volatile("" : "+v"(qf[ks]));
.LBB0_1171:
	s_ashr_i32 s17, s3, 8
	s_and_b32 s6, s3, 1
	s_cmp_lt_i32 s17, 2
	s_cselect_b32 s16, 7, 3
	s_cmp_eq_u32 s6, 0
	s_cselect_b32 s41, s16, 5
	s_sub_i32 s40, s41, s17
	s_lshl_b32 s6, s3, 7
	s_and_b32 s16, s6, 0x7800
	s_lshl_b32 s57, s40, 8
	v_readlane_b32 s6, v254, 20
	v_mov_b32_e32 v0, v223
	s_add_i32 s57, s57, s6
	s_bfe_u32 s38, s3, 0x30001
	s_add_i32 s6, s57, s16
	v_and_b32_e32 v50, 31, v0
	v_or_b32_e32 v2, s6, v50
	s_lshl_b32 s56, s38, 7
	v_ashrrev_i32_e32 v33, 3, v0
	v_mad_i64_i32 v[2:3], s[36:37], v2, s0, v[204:205]
	s_mul_i32 s6, s38, 0x180
	v_ashrrev_i32_e32 v32, 4, v0
	v_add_u32_e32 v6, s56, v33
	v_lshl_add_u64 v[22:23], v[2:3], 0, s[6:7]
	v_add_u32_e32 v2, s16, v32
	v_ashrrev_i32_e32 v7, 31, v6
	v_ashrrev_i32_e32 v3, 31, v2
	v_lshlrev_b64 v[6:7], 16, v[6:7]
	v_lshlrev_b64 v[2:3], 11, v[2:3]
	v_add_u32_e32 v4, s16, v33
	v_lshl_add_u64 v[6:7], s[34:35], 0, v[6:7]
	s_lshl_b32 s6, s16, 1
	v_ashrrev_i32_e32 v5, 31, v4
	v_lshl_add_u64 v[6:7], v[6:7], 0, s[6:7]
	v_lshlrev_b32_e32 v8, 4, v0
	v_lshl_add_u64 v[2:3], s[14:15], 0, v[2:3]
	s_lshl_b32 s6, s38, 8
	v_lshlrev_b64 v[4:5], 7, v[4:5]
	v_and_b32_e32 v26, 0xf0, v8
	v_lshl_add_u64 v[2:3], v[2:3], 0, s[6:7]
	v_mov_b32_e32 v27, v1
	v_and_b32_e32 v24, 0x70, v8
	v_mov_b32_e32 v25, v1
	v_lshl_add_u64 v[208:209], v[2:3], 0, v[26:27]
	v_lshl_add_u64 v[2:3], s[48:49], 0, v[4:5]
	v_lshl_add_u64 v[210:211], v[2:3], 0, v[24:25]
	v_add_co_u32_e32 v2, vcc, s42, v208
	v_lshl_add_u64 v[206:207], v[6:7], 0, v[24:25]
	s_nop 0
	v_addc_co_u32_e32 v3, vcc, 0, v209, vcc
	v_add_co_u32_e32 v18, vcc, s43, v206
	global_load_dwordx4 v[2:5], v[2:3], off
	s_nop 0
	global_load_dwordx4 v[6:9], v[210:211], off
	global_load_dwordx4 v[10:13], v[208:209], off
	global_load_dwordx4 v[14:17], v[206:207], off
	v_addc_co_u32_e32 v19, vcc, 0, v207, vcc
	v_add_co_u32_e32 v28, vcc, s45, v208
	v_bfe_u32 v51, v0, 5, 1
	s_nop 0
	v_addc_co_u32_e32 v29, vcc, 0, v209, vcc
	global_load_dwordx4 v[18:21], v[18:19], off
	s_nop 0
	global_load_dwordx4 v[176:179], v[28:29], off
	v_add_co_u32_e32 v28, vcc, s50, v208
	v_lshlrev_b32_e32 v0, 4, v51
	s_nop 0
	v_addc_co_u32_e32 v29, vcc, 0, v209, vcc
	v_add_co_u32_e32 v30, vcc, s51, v210
	v_lshl_add_u64 v[22:23], v[22:23], 0, v[0:1]
	s_nop 0
	v_addc_co_u32_e32 v31, vcc, 0, v211, vcc
	global_load_dwordx4 v[180:183], v[28:29], off
	global_load_dwordx4 v[184:187], v[30:31], off
	global_load_dwordx4 v[128:131], v[22:23], off
	global_load_dwordx4 v[132:135], v[22:23], off offset:32
	global_load_dwordx4 v[136:139], v[22:23], off offset:64
	global_load_dwordx4 v[140:143], v[22:23], off offset:96
	global_load_dwordx4 v[144:147], v[22:23], off offset:128
	global_load_dwordx4 v[148:151], v[22:23], off offset:160
	global_load_dwordx4 v[152:155], v[22:23], off offset:192
	global_load_dwordx4 v[156:159], v[22:23], off offset:224
	global_load_dwordx4 v[160:163], v[22:23], off offset:256
	global_load_dwordx4 v[164:167], v[22:23], off offset:288
	global_load_dwordx4 v[168:171], v[22:23], off offset:320
	global_load_dwordx4 v[172:175], v[22:23], off offset:352
	v_mad_u64_u32 v[212:213], s[36:37], v32, s27, v[26:27]
	v_mul_lo_u32 v22, v33, s1
	v_add_u32_e32 v23, 0, v212
	v_mad_u64_u32 v[214:215], s[36:37], v33, s27, v[24:25]
	s_cmp_lg_u32 s41, s17
	s_cselect_b64 s[36:37], -1, 0
	s_mov_b64 s[38:39], -1
	s_and_b64 vcc, exec, s[36:37]
	s_waitcnt vmcnt(17)
	ds_write_b128 v23, v[10:13]
	ds_write_b128 v23, v[2:5] offset:12800
	v_add_u32_e32 v3, 0, v22
	v_add3_u32 v213, v3, v24, s44
	v_add_u32_e32 v2, 0, v214
	v_add_u32_e32 v3, 0x2200, v213
	ds_write_b128 v2, v[6:9] offset:256
	s_waitcnt vmcnt(16)
	ds_write2_b64 v213, v[14:15], v[16:17] offset1:1
	s_waitcnt vmcnt(15)
	ds_write2_b64 v3, v[18:19], v[20:21] offset1:1
	s_waitcnt vmcnt(14)
	ds_write_b128 v23, v[176:179] offset:25600
	s_waitcnt vmcnt(13)
	ds_write_b128 v23, v[180:183] offset:38400
	s_waitcnt vmcnt(12)
	ds_write_b128 v2, v[184:187] offset:25856
	v_mul_u32_u24_e32 v2, 0x190, v50
	v_add3_u32 v215, 0, v2, v0
	s_waitcnt lgkmcnt(0)
	s_barrier
	ds_read_b128 v[2:5], v215
	ds_read_b128 v[34:37], v215 offset:32
	s_waitcnt lgkmcnt(1)
	s_waitcnt vmcnt(11)
	v_mfma_f32_32x32x16_bf16 v[2:17], v[2:5], v[128:131], 0
	ds_read_b128 v[18:21], v215 offset:12800
	ds_read_b128 v[38:41], v215 offset:12832
	s_waitcnt lgkmcnt(1)
	v_mfma_f32_32x32x16_bf16 v[18:33], v[18:21], v[128:131], 0
	s_waitcnt vmcnt(10)
	v_mfma_f32_32x32x16_bf16 v[2:17], v[34:37], v[132:135], v[2:17]
	s_waitcnt lgkmcnt(0)
	v_mfma_f32_32x32x16_bf16 v[18:33], v[38:41], v[132:135], v[18:33]
	ds_read_b128 v[34:37], v215 offset:64
	ds_read_b128 v[38:41], v215 offset:96
	s_waitcnt lgkmcnt(1)
	s_waitcnt vmcnt(9)
	v_mfma_f32_32x32x16_bf16 v[2:17], v[34:37], v[136:139], v[2:17]
	ds_read_b128 v[34:37], v215 offset:12864
	ds_read_b128 v[42:45], v215 offset:12896
	s_waitcnt lgkmcnt(1)
	v_mfma_f32_32x32x16_bf16 v[18:33], v[34:37], v[136:139], v[18:33]
	s_waitcnt vmcnt(8)
	v_mfma_f32_32x32x16_bf16 v[2:17], v[38:41], v[140:143], v[2:17]
	ds_read_b128 v[34:37], v215 offset:128
	ds_read_b128 v[38:41], v215 offset:160
	s_waitcnt lgkmcnt(2)
	v_mfma_f32_32x32x16_bf16 v[18:33], v[42:45], v[140:143], v[18:33]
	s_waitcnt lgkmcnt(1)
	s_waitcnt vmcnt(7)
	v_mfma_f32_32x32x16_bf16 v[2:17], v[34:37], v[144:147], v[2:17]
	ds_read_b128 v[34:37], v215 offset:12928
	ds_read_b128 v[42:45], v215 offset:12960
	s_waitcnt lgkmcnt(1)
	v_mfma_f32_32x32x16_bf16 v[18:33], v[34:37], v[144:147], v[18:33]
	s_waitcnt vmcnt(6)
	v_mfma_f32_32x32x16_bf16 v[2:17], v[38:41], v[148:151], v[2:17]
	ds_read_b128 v[34:37], v215 offset:192
	ds_read_b128 v[38:41], v215 offset:224
	s_waitcnt lgkmcnt(2)
	v_mfma_f32_32x32x16_bf16 v[18:33], v[42:45], v[148:151], v[18:33]
	s_waitcnt lgkmcnt(1)
; __device__ __forceinline__ void unit(LAS unsigned char* lds, int b, int h, int qb, const bf16_t* Q, const bf16_t* Kn, const bf16_t* Kr, const bf16_t* VT, const bf16_t* proj, bf16_t* ymix, int wv) {
;     ...
;     ATT_QK(0);
;     if (NT <= 4) ATT_SMA(0, true); else ATT_SMA(0, false);
;     pf[0][0] = pf2[0][0]; pf[0][1] = pf2[0][1]; pf[1][0] = pf2[1][0]; pf[1][1] = pf2[1][1];
	s_waitcnt vmcnt(5)
	v_mfma_f32_32x32x16_bf16 v[2:17], v[34:37], v[152:155], v[2:17]
	ds_read_b128 v[34:37], v215 offset:12992
	ds_read_b128 v[42:45], v215 offset:13024
	s_waitcnt lgkmcnt(1)
	v_mfma_f32_32x32x16_bf16 v[18:33], v[34:37], v[152:155], v[18:33]
	s_waitcnt vmcnt(4)
	v_mfma_f32_32x32x16_bf16 v[2:17], v[38:41], v[156:159], v[2:17]
	ds_read_b128 v[34:37], v215 offset:256
	ds_read_b128 v[38:41], v215 offset:288
	s_waitcnt lgkmcnt(2)
	v_mfma_f32_32x32x16_bf16 v[18:33], v[42:45], v[156:159], v[18:33]
	s_waitcnt lgkmcnt(1)
	s_waitcnt vmcnt(3)
	v_mfma_f32_32x32x16_bf16 v[2:17], v[34:37], v[160:163], v[2:17]
	ds_read_b128 v[34:37], v215 offset:13056
	ds_read_b128 v[42:45], v215 offset:13088
	s_waitcnt lgkmcnt(1)
	v_mfma_f32_32x32x16_bf16 v[18:33], v[34:37], v[160:163], v[18:33]
	s_waitcnt vmcnt(2)
	v_mfma_f32_32x32x16_bf16 v[2:17], v[38:41], v[164:167], v[2:17]
	ds_read_b128 v[34:37], v215 offset:320
	ds_read_b128 v[38:41], v215 offset:352
	s_waitcnt lgkmcnt(2)
	v_mfma_f32_32x32x16_bf16 v[18:33], v[42:45], v[164:167], v[18:33]
	s_waitcnt lgkmcnt(1)
	s_waitcnt vmcnt(1)
	v_mfma_f32_32x32x16_bf16 v[2:17], v[34:37], v[168:171], v[2:17]
	ds_read_b128 v[34:37], v215 offset:13120
	ds_read_b128 v[42:45], v215 offset:13152
	s_waitcnt lgkmcnt(1)
	v_mfma_f32_32x32x16_bf16 v[18:33], v[34:37], v[168:171], v[18:33]
	s_waitcnt vmcnt(0)
	v_mfma_f32_32x32x16_bf16 v[2:17], v[38:41], v[172:175], v[2:17]
	s_waitcnt lgkmcnt(0)
	v_mfma_f32_32x32x16_bf16 v[18:33], v[42:45], v[172:175], v[18:33]
	s_cbranch_vccz .LBB0_1173
	s_nop 10
	v_max_f32_e32 v0, v19, v19
	v_max_f32_e32 v34, v3, v3
	v_max_f32_e32 v0, v34, v0
	v_max_f32_e32 v34, v20, v20
	v_max_f32_e32 v35, v4, v4
	v_max_f32_e32 v34, v35, v34
	v_max_f32_e32 v35, v21, v21
	v_max_f32_e32 v36, v5, v5
	v_max3_f32 v0, v2, v18, v0
	v_max_f32_e32 v35, v36, v35
	v_max3_f32 v0, v0, v34, v35
	v_max_f32_e32 v34, v22, v22
	v_max_f32_e32 v35, v6, v6
	v_max_f32_e32 v34, v35, v34
	v_max_f32_e32 v35, v23, v23
	v_max_f32_e32 v36, v7, v7
	v_max_f32_e32 v35, v36, v35
	v_max3_f32 v0, v0, v34, v35
	v_max_f32_e32 v34, v24, v24
	v_max_f32_e32 v35, v8, v8
	v_max_f32_e32 v34, v35, v34
	v_max_f32_e32 v35, v25, v25
	v_max_f32_e32 v36, v9, v9
	v_max_f32_e32 v35, v36, v35
	v_max3_f32 v0, v0, v34, v35
	v_max_f32_e32 v34, v26, v26
	v_max_f32_e32 v35, v10, v10
	v_max_f32_e32 v34, v35, v34
	v_max_f32_e32 v35, v27, v27
	v_max_f32_e32 v36, v11, v11
	v_max_f32_e32 v35, v36, v35
	v_max3_f32 v0, v0, v34, v35
	v_max_f32_e32 v34, v28, v28
	v_max_f32_e32 v35, v12, v12
	v_max_f32_e32 v34, v35, v34
	v_max_f32_e32 v35, v29, v29
	v_max_f32_e32 v36, v13, v13
	v_max_f32_e32 v35, v36, v35
	v_max3_f32 v0, v0, v34, v35
	v_max_f32_e32 v34, v30, v30
	v_max_f32_e32 v35, v14, v14
	v_max_f32_e32 v34, v35, v34
	v_max_f32_e32 v35, v31, v31
	v_max_f32_e32 v36, v15, v15
	v_max_f32_e32 v35, v36, v35
	v_max3_f32 v0, v0, v34, v35
	v_max_f32_e32 v34, v32, v32
	v_max_f32_e32 v35, v16, v16
	v_max_f32_e32 v34, v35, v34
	v_max_f32_e32 v35, v33, v33
	v_max_f32_e32 v36, v17, v17
	v_max_f32_e32 v35, v36, v35
	v_max3_f32 v0, v0, v34, v35
	v_mov_b32_e32 v34, v222
	s_mov_b64 s[38:39], 0
	v_lshlrev_b32_e32 v34, 2, v34
	v_xor_b32_e32 v34, 0x80, v34
	ds_bpermute_b32 v34, v34, v0
	s_waitcnt lgkmcnt(0)
	v_max3_f32 v217, v0, v34, s52
	v_sub_f32_e32 v34, v2, v217
	v_sub_f32_e32 v42, v10, v217
	v_exp_f32_e32 v52, v34
	v_sub_f32_e32 v34, v18, v217
	v_exp_f32_e32 v68, v42
	v_sub_f32_e32 v42, v26, v217
	v_exp_f32_e32 v54, v34
	v_sub_f32_e32 v34, v3, v217
	v_exp_f32_e32 v70, v42
	v_sub_f32_e32 v42, v11, v217
	v_exp_f32_e32 v53, v34
	v_sub_f32_e32 v34, v19, v217
	v_exp_f32_e32 v69, v42
	v_sub_f32_e32 v42, v27, v217
	v_exp_f32_e32 v55, v34
	v_sub_f32_e32 v34, v4, v217
	v_exp_f32_e32 v71, v42
	v_sub_f32_e32 v42, v12, v217
	v_exp_f32_e32 v56, v34
	v_sub_f32_e32 v34, v20, v217
	v_exp_f32_e32 v72, v42
	v_sub_f32_e32 v42, v28, v217
	v_exp_f32_e32 v58, v34
	v_sub_f32_e32 v34, v5, v217
	v_exp_f32_e32 v74, v42
	v_sub_f32_e32 v42, v13, v217
	v_exp_f32_e32 v57, v34
	v_sub_f32_e32 v34, v21, v217
	v_exp_f32_e32 v73, v42
	v_sub_f32_e32 v42, v29, v217
	v_exp_f32_e32 v59, v34
	v_sub_f32_e32 v34, v6, v217
	v_exp_f32_e32 v75, v42
	v_sub_f32_e32 v42, v14, v217
	v_exp_f32_e32 v60, v34
	v_sub_f32_e32 v34, v22, v217
	v_exp_f32_e32 v76, v42
	v_sub_f32_e32 v42, v30, v217
	v_exp_f32_e32 v62, v34
	v_sub_f32_e32 v34, v7, v217
	v_exp_f32_e32 v78, v42
	v_sub_f32_e32 v42, v15, v217
	v_exp_f32_e32 v61, v34
	v_sub_f32_e32 v34, v23, v217
	v_exp_f32_e32 v77, v42
	v_sub_f32_e32 v42, v31, v217
	v_exp_f32_e32 v63, v34
	v_sub_f32_e32 v34, v8, v217
	v_exp_f32_e32 v79, v42
	v_sub_f32_e32 v42, v16, v217
	v_exp_f32_e32 v64, v34
	v_sub_f32_e32 v34, v24, v217
	v_exp_f32_e32 v80, v42
	v_sub_f32_e32 v42, v32, v217
	v_exp_f32_e32 v66, v34
	v_sub_f32_e32 v34, v9, v217
	v_exp_f32_e32 v82, v42
	v_sub_f32_e32 v42, v17, v217
	v_exp_f32_e32 v65, v34
	v_sub_f32_e32 v34, v25, v217
	v_exp_f32_e32 v81, v42
	v_sub_f32_e32 v42, v33, v217
	v_exp_f32_e32 v67, v34
	v_exp_f32_e32 v83, v42
	v_sub_f32_e32 v0, 0xff800000, v217
	v_pk_add_f32 v[38:39], v[54:55], v[52:53]
	v_pk_add_f32 v[36:37], v[58:59], v[56:57]
	v_pk_add_f32 v[34:35], v[62:63], v[60:61]
	v_pk_add_f32 v[40:41], v[66:67], v[64:65]
	v_pk_add_f32 v[46:47], v[70:71], v[68:69]
	v_pk_add_f32 v[44:45], v[74:75], v[72:73]
	v_pk_add_f32 v[42:43], v[78:79], v[76:77]
	v_pk_add_f32 v[48:49], v[82:83], v[80:81]
	v_exp_f32_e32 v0, v0
	v_cvt_pk_bf16_f32 v200, v52, v53
	v_cvt_pk_bf16_f32 v201, v56, v57
	v_cvt_pk_bf16_f32 v202, v60, v61
	v_cvt_pk_bf16_f32 v203, v64, v65
	v_cvt_pk_bf16_f32 v192, v54, v55
	v_cvt_pk_bf16_f32 v193, v58, v59
	v_cvt_pk_bf16_f32 v194, v62, v63
	v_cvt_pk_bf16_f32 v195, v66, v67
	v_cvt_pk_bf16_f32 v196, v68, v69
	v_cvt_pk_bf16_f32 v197, v72, v73
	v_cvt_pk_bf16_f32 v198, v76, v77
	v_cvt_pk_bf16_f32 v199, v80, v81
	v_cvt_pk_bf16_f32 v188, v70, v71
	v_cvt_pk_bf16_f32 v189, v74, v75
	v_cvt_pk_bf16_f32 v190, v78, v79
	v_cvt_pk_bf16_f32 v191, v82, v83
